# v47 + gate/up GEMM: epilogue stores not drained at tile start (peeled body's first two segment waits count them)
# speedup vs baseline: 1.0091x; 1.0091x over previous
; #define PG8_STAGE(bufoff, gbase, voff) do { _Pragma("unroll") for (int _i = 0; _i < 2; ++_i) \
;         __builtin_amdgcn_global_load_lds((const unsigned*)((const char*)(gbase) + (voff)[_i]), (PG8_LAS unsigned*)(lds + (bufoff) + ldsw + _i * 8192), 16, 0, 0); } while (0)
; #define PG8_WAIT_V(n) asm volatile("s_waitcnt vmcnt(" #n ")" ::: "memory")
; #define PG8_BAR __builtin_amdgcn_s_barrier()
; template <class Epi, class Sched, bool ALIGN_EPI = false, bool SP2 = false, bool F16 = false>
; __device__ __forceinline__ void gemm_phase(PG8_LAS unsigned char* lds, const Gemm g, const Sched& S, const Epi& E) {
;     ...
;     for (int i = 0; i < 2; ++i) { int R, C; stage_rc(tid * 16 + i * 8192, R, C); const int Rb = Epi::PERM ? ((R & ~31) + perm32(R & 31)) : R;
;         voffA[i] = (unsigned)(R * K + C) * 2u; voffB[i] = (unsigned)(Rb * K + C) * 2u; }
;     const size_t kstep = (size_t)(BK * 2);
;     const size_t hstep = (size_t)HALF * K * 2;
;     const size_t tstep = 2 * hstep;
;     const unsigned ldsw = (unsigned)wid * 1024u;
;     const int aoff = lds_byte(wr * 64 + fr, fq * 8), boff = lds_byte(wc * 32 + fr, fq * 8);
;     ...
;         PG8_STAGE(PG8_SB(0, 0), cB, voffB); PG8_STAGE(PG8_SB(0, 1), cB + hstep, voffB); PG8_STAGE(PG8_SA(0, 0), cA, voffA); PG8_STAGE(PG8_SA(0, 1), cA + hstep, voffA);
;         if (wr == 1) PG8_BAR;
;         PG8_WAIT_V(2); PG8_BAR;
;         PG8_STAGE(PG8_SB(1, 0), cB + kstep, voffB); PG8_STAGE(PG8_SA(1, 0), cA + kstep, voffA); PG8_STAGE(PG8_SB(1, 1), cB + hstep + kstep, voffB);
;         PG8_WAIT_V(6); PG8_BAR;
.LBB0_898:
	v_readlane_b32 s14, v255, 14
	v_readlane_b32 s15, v255, 15
	s_lshl_b32 s34, s14, 16
	s_mov_b32 s30, s14
	s_lshl_b64 s[14:15], s[34:35], 2
	v_readlane_b32 s12, v252, 48
	s_add_u32 s14, s12, s14
	s_addc_u32 s15, s28, s15
	s_add_u32 s42, s14, 0x20000
	s_addc_u32 s43, s15, 0
	s_mul_i32 s14, s30, 0xb000
	v_readlane_b32 s12, v254, 19
	s_add_u32 s14, s12, s14
	v_readlane_b32 s12, v254, 20
	v_readlane_b32 s54, v254, 32
	s_addc_u32 s15, s12, 0
	s_lshl_b32 s20, s20, 5
	v_mov_b32_e32 v151, v129
	v_readlane_b32 s55, v254, 33
	s_and_b32 s34, s20, 0x60
	s_add_i32 m0, s9, 0x18000
	v_lshl_add_u64 v[0:1], v[0:1], 0, s[16:17]
	v_lshl_add_u64 v[12:13], s[54:55], 0, v[150:151]
	v_mov_b32_e32 v149, v129
	s_lshl_b32 s29, s5, 13
	s_lshl_b32 s37, s34, 7
	s_waitcnt vmcnt(2)
	s_barrier
	global_load_lds_dwordx4 v[0:1], off
	v_lshl_add_u64 v[0:1], v[2:3], 0, s[16:17]
	s_add_i32 m0, s9, 0x1a000
	s_add_i32 s20, s9, 0x8000
	s_add_i32 s21, s9, 0xa000
	v_lshl_add_u64 v[14:15], s[54:55], 0, v[148:149]
	global_load_lds_dwordx4 v[0:1], off
	v_lshl_add_u64 v[0:1], v[12:13], 0, s[16:17]
	s_mov_b32 m0, s20
	s_add_u32 s30, s56, 0x40080
	global_load_lds_dwordx4 v[0:1], off
	v_lshl_add_u64 v[0:1], v[14:15], 0, s[16:17]
	s_mov_b32 m0, s21
	s_addc_u32 s31, s57, 0
	global_load_lds_dwordx4 v[0:1], off
	s_add_i32 m0, s9, 0x1c000
	v_lshl_add_u64 v[0:1], s[30:31], 0, v[128:129]
	global_load_lds_dwordx4 v[0:1], off
	v_lshl_add_u64 v[0:1], s[30:31], 0, v[146:147]
	s_add_i32 m0, s9, 0x1e000
	s_cmpk_lt_u32 s4, 0x100
	global_load_lds_dwordx4 v[0:1], off
	v_lshrrev_b32_e32 v0, 1, v4
	v_and_b32_e32 v0, 24, v0
	v_and_b32_e32 v1, 15, v4
	v_lshlrev_b32_e32 v2, 1, v0
	v_lshl_or_b32 v162, s5, 6, v1
	v_lshl_or_b32 v1, v1, 6, v2
	v_lshlrev_b32_e32 v2, 2, v4
	v_and_b32_e32 v2, 32, v2
	v_bitop3_b32 v3, v1, s29, v2 bitop3:0xde
	v_bitop3_b32 v163, v1, s37, v2 bitop3:0xde
	v_lshlrev_b32_e32 v1, 14, v9
	v_and_b32_e32 v1, 0xffff8000, v1
	v_lshl_add_u32 v1, v8, 11, v1
	v_and_b32_e32 v2, 1, v9
	v_lshl_or_b32 v1, v2, 6, v1
	v_lshl_add_u32 v152, v10, 1, v1
	v_lshlrev_b32_e32 v1, 14, v5
	v_and_b32_e32 v1, 0xffff8000, v1
	s_waitcnt vmcnt(6)
	v_lshl_add_u32 v1, v6, 11, v1
	v_and_b32_e32 v2, 1, v5
	v_lshl_or_b32 v1, v2, 6, v1
	v_readlane_b32 s4, v254, 29
	s_cselect_b64 s[44:45], -1, 0
	v_or_b32_e32 v164, s34, v0
	v_mov_b32_e32 v153, v129
	v_lshl_add_u32 v154, v7, 1, v1
	v_mov_b32_e32 v155, v129
	s_mov_b32 s29, 0
	v_add_u32_e32 v165, 0, v3
	s_lshl_b32 s30, s34, 2
	v_lshlrev_b32_e32 v166, 2, v0
	v_readlane_b32 s31, v254, 25
	s_mov_b32 s34, s4
	s_waitcnt vmcnt(0)
	s_barrier
	v_readlane_b32 s5, v254, 30
	s_branch .LBB0_901

; #define PG8_STAGE(bufoff, gbase, voff) do { _Pragma("unroll") for (int _i = 0; _i < 2; ++_i) \
;         __builtin_amdgcn_global_load_lds((const unsigned*)((const char*)(gbase) + (voff)[_i]), (PG8_LAS unsigned*)(lds + (bufoff) + ldsw + _i * 8192), 16, 0, 0); } while (0)
; #define PG8_LDA(dst, b, h) do { _Pragma("unroll") for (int m = 0; m < 4; ++m) _Pragma("unroll") for (int k = 0; k < 2; ++k) dst[m][k] = *(const PG8_LAS bf16x8*)(lds + PG8_SA(b, h) + aoff + m * 2048 + k * 1024); } while (0)
; #define PG8_LDB(dst, b, h) do { _Pragma("unroll") for (int n = 0; n < 2; ++n) _Pragma("unroll") for (int k = 0; k < 2; ++k) dst[n][k] = *(const PG8_LAS bf16x8*)(lds + PG8_SB(b, h) + boff + n * 2048 + k * 1024); } while (0)
; #define PG8_MMA(ai, bj, At, Bt) do { __builtin_amdgcn_s_setprio(1); _Pragma("unroll") for (int m = 0; m < 4; ++m) _Pragma("unroll") for (int n = 0; n < 2; ++n) _Pragma("unroll") for (int k = 0; k < 2; ++k) \
;         acc[ai][bj][m][n] = mma16<F16>(Bt[n][k], At[m][k], acc[ai][bj][m][n]); __builtin_amdgcn_s_setprio(0); } while (0)
; #define PG8_WAIT_V(n) asm volatile("s_waitcnt vmcnt(" #n ")" ::: "memory")
; #define PG8_WAIT_L(n) asm volatile("s_waitcnt lgkmcnt(" #n ")" ::: "memory")
; #define PG8_BAR __builtin_amdgcn_s_barrier()
; #define PG8_SCHED __builtin_amdgcn_sched_barrier(0)
; template <class Epi, class Sched, bool ALIGN_EPI = false, bool SP2 = false, bool F16 = false>
; __device__ __forceinline__ void gemm_phase(PG8_LAS unsigned char* lds, const Gemm g, const Sched& S, const Epi& E) {
;     ...
;             PG8_LDB(B0, 0, 0); PG8_LDB(B1, 0, 1); PG8_SCHED; PG8_LDA(At, 0, 0); PG8_STAGE(PG8_SA(1, 1), a1 + hstep, voffA);
;             PG8_WAIT_V(8); PG8_WAIT_L(0); PG8_BAR; PG8_MMA(0, 0, At, B0); PG8_MMA(0, 1, At, B1); PG8_BAR; PG8_SCHED;
;             PG8_LDA(At, 0, 1); PG8_STAGE(PG8_SB(0, 0), b2, voffB); PG8_STAGE(PG8_SB(0, 1), b2 + hstep, voffB); PG8_STAGE(PG8_SA(0, 0), a2, voffA);
;             PG8_WAIT_V(8); PG8_WAIT_L(0); PG8_BAR; PG8_MMA(1, 0, At, B0); PG8_MMA(1, 1, At, B1); PG8_BAR; PG8_SCHED;
.LBB0_903:
	s_ashr_i32 s49, s48, 31
	s_lshl_b64 s[4:5], s[48:49], 19
	s_add_u32 s50, s96, s4
	s_addc_u32 s51, s97, s5
	s_and_b64 s[4:5], s[40:41], exec
	s_cselect_b32 s4, s51, s55
	s_cselect_b32 s5, s50, s54
	s_ashr_i32 s47, s46, 31
	s_lshl_b64 s[52:53], s[46:47], 19
	s_add_u32 s37, s6, s52
	s_addc_u32 s47, s7, s53
	s_cmp_gt_i32 s48, 63
	s_cselect_b32 s49, 0xb00000, 0
	s_add_u32 s52, s37, s49
	s_addc_u32 s53, s47, 0
	s_and_b64 s[58:59], s[40:41], exec
	s_cselect_b32 s37, s53, s57
	s_cselect_b32 s47, s52, s56
	s_add_u32 s54, s54, 0x40080
	s_addc_u32 s55, s55, 0
	s_add_u32 s49, s56, 0x100
	s_addc_u32 s60, s57, 0
	s_mov_b32 s61, -2
	v_add_u32_e32 v172, 0x10000, v163
	s_add_u32 s56, s54, 0xfffc0080
	s_addc_u32 s57, s55, -1
	s_add_i32 s62, 0, 0x10000
	s_cmp_eq_u32 s61, 12
	s_cselect_b32 s59, s4, s57
	s_cselect_b32 s58, s5, s56
	s_cselect_b32 s57, s37, s60
	s_cselect_b32 s56, s47, s49
	s_add_i32 s64, 0, 0x14000
	ds_read_b128 v[32:35], v172
	ds_read_b128 v[36:39], v172 offset:1024
	ds_read_b128 v[40:43], v172 offset:2048
	ds_read_b128 v[44:47], v172 offset:3072
	ds_read_b128 v[156:159], v172 offset:16384
	ds_read_b128 v[168:171], v172 offset:17408
	ds_read_b128 v[186:189], v172 offset:18432
	ds_read_b128 v[190:193], v172 offset:19456
	s_add_i32 m0, s9, 0xc000
	ds_read_b128 v[194:197], v165
	ds_read_b128 v[198:201], v165 offset:1024
	ds_read_b128 v[202:205], v165 offset:2048
	ds_read_b128 v[206:209], v165 offset:3072
	ds_read_b128 v[210:213], v165 offset:4096
	ds_read_b128 v[214:217], v165 offset:5120
	ds_read_b128 v[218:221], v165 offset:6144
	ds_read_b128 v[222:225], v165 offset:7168
	global_load_lds_dwordx4 v152, s[54:55]
	s_add_i32 m0, s9, 0xe000
	s_nop 0
	global_load_lds_dwordx4 v154, s[54:55]
	s_waitcnt vmcnt(16)
	s_waitcnt lgkmcnt(0)
	s_barrier
	s_setprio 1
	s_waitcnt lgkmcnt(0)
	v_mfma_f32_16x16x32_f16 v[142:145], v[32:35], v[194:197], 0
	v_mfma_f32_16x16x32_f16 v[138:141], v[40:43], v[194:197], 0
	v_mfma_f32_16x16x32_f16 v[124:127], v[32:35], v[202:205], 0
	v_mfma_f32_16x16x32_f16 v[120:123], v[40:43], v[202:205], 0
	v_mfma_f32_16x16x32_f16 v[108:111], v[32:35], v[210:213], 0
	v_mfma_f32_16x16x32_f16 v[104:107], v[40:43], v[210:213], 0
	v_mfma_f32_16x16x32_f16 v[92:95], v[32:35], v[218:221], 0
	v_mfma_f32_16x16x32_f16 v[88:91], v[40:43], v[218:221], 0
	v_mfma_f32_16x16x32_f16 v[142:145], v[36:39], v[198:201], v[142:145]
	v_mfma_f32_16x16x32_f16 v[138:141], v[44:47], v[198:201], v[138:141]
	v_mfma_f32_16x16x32_f16 v[124:127], v[36:39], v[206:209], v[124:127]
	v_mfma_f32_16x16x32_f16 v[120:123], v[44:47], v[206:209], v[120:123]
	v_mfma_f32_16x16x32_f16 v[108:111], v[36:39], v[214:217], v[108:111]
	v_mfma_f32_16x16x32_f16 v[104:107], v[44:47], v[214:217], v[104:107]
	v_mfma_f32_16x16x32_f16 v[92:95], v[36:39], v[222:225], v[92:95]
	v_mfma_f32_16x16x32_f16 v[88:91], v[44:47], v[222:225], v[88:91]
	v_mfma_f32_16x16x32_f16 v[134:137], v[156:159], v[194:197], 0
	v_mfma_f32_16x16x32_f16 v[130:133], v[186:189], v[194:197], 0
	v_mfma_f32_16x16x32_f16 v[116:119], v[156:159], v[202:205], 0
	v_mfma_f32_16x16x32_f16 v[112:115], v[186:189], v[202:205], 0
	v_mfma_f32_16x16x32_f16 v[100:103], v[156:159], v[210:213], 0
	v_mfma_f32_16x16x32_f16 v[96:99], v[186:189], v[210:213], 0
	v_mfma_f32_16x16x32_f16 v[84:87], v[156:159], v[218:221], 0
	v_mfma_f32_16x16x32_f16 v[80:83], v[186:189], v[218:221], 0
	v_mfma_f32_16x16x32_f16 v[134:137], v[168:171], v[198:201], v[134:137]
	v_mfma_f32_16x16x32_f16 v[130:133], v[190:193], v[198:201], v[130:133]
	v_mfma_f32_16x16x32_f16 v[116:119], v[168:171], v[206:209], v[116:119]
	v_mfma_f32_16x16x32_f16 v[112:115], v[190:193], v[206:209], v[112:115]
	v_mfma_f32_16x16x32_f16 v[100:103], v[168:171], v[214:217], v[100:103]
	v_mfma_f32_16x16x32_f16 v[96:99], v[190:193], v[214:217], v[96:99]
	v_mfma_f32_16x16x32_f16 v[84:87], v[168:171], v[222:225], v[84:87]
	v_mfma_f32_16x16x32_f16 v[80:83], v[190:193], v[222:225], v[80:83]
	s_setprio 0
	s_barrier
	s_add_u32 s98, s56, s16
	s_addc_u32 s99, s57, s17
	s_add_u32 s100, s58, s16
	s_addc_u32 s101, s59, s17
	s_add_i32 s62, s62, s8
	s_mov_b32 m0, s62
	ds_read_b128 v[194:197], v165 offset:16384
	ds_read_b128 v[198:201], v165 offset:17408
	ds_read_b128 v[202:205], v165 offset:18432
	ds_read_b128 v[206:209], v165 offset:19456
	ds_read_b128 v[210:213], v165 offset:20480
	ds_read_b128 v[214:217], v165 offset:21504
	ds_read_b128 v[218:221], v165 offset:22528
	ds_read_b128 v[222:225], v165 offset:23552
	global_load_lds_dwordx4 v128, s[56:57]
	s_add_i32 m0, s62, 0x2000
	s_add_u32 s62, s56, 0x40000
	s_addc_u32 s63, s57, 0
	s_add_i32 s64, s64, s8
	global_load_lds_dwordx4 v146, s[56:57]
	s_mov_b32 m0, s64
	s_nop 0
	global_load_lds_dwordx4 v128, s[62:63]
	s_add_i32 m0, s64, 0x2000
	s_nop 0
	global_load_lds_dwordx4 v146, s[62:63]
	s_mov_b32 m0, s9
	s_nop 0
	global_load_lds_dwordx4 v150, s[58:59]
	s_mov_b32 m0, s10
	s_nop 0
	global_load_lds_dwordx4 v148, s[58:59]
	s_waitcnt vmcnt(16)
	s_waitcnt lgkmcnt(0)
	s_barrier
; #define PG8_STAGE(bufoff, gbase, voff) do { _Pragma("unroll") for (int _i = 0; _i < 2; ++_i) \
;         __builtin_amdgcn_global_load_lds((const unsigned*)((const char*)(gbase) + (voff)[_i]), (PG8_LAS unsigned*)(lds + (bufoff) + ldsw + _i * 8192), 16, 0, 0); } while (0)
; #define PG8_LDA(dst, b, h) do { _Pragma("unroll") for (int m = 0; m < 4; ++m) _Pragma("unroll") for (int k = 0; k < 2; ++k) dst[m][k] = *(const PG8_LAS bf16x8*)(lds + PG8_SA(b, h) + aoff + m * 2048 + k * 1024); } while (0)
; #define PG8_LDB(dst, b, h) do { _Pragma("unroll") for (int n = 0; n < 2; ++n) _Pragma("unroll") for (int k = 0; k < 2; ++k) dst[n][k] = *(const PG8_LAS bf16x8*)(lds + PG8_SB(b, h) + boff + n * 2048 + k * 1024); } while (0)
; #define PG8_MMA(ai, bj, At, Bt) do { __builtin_amdgcn_s_setprio(1); _Pragma("unroll") for (int m = 0; m < 4; ++m) _Pragma("unroll") for (int n = 0; n < 2; ++n) _Pragma("unroll") for (int k = 0; k < 2; ++k) \
;         acc[ai][bj][m][n] = mma16<F16>(Bt[n][k], At[m][k], acc[ai][bj][m][n]); __builtin_amdgcn_s_setprio(0); } while (0)
; #define PG8_WAIT_V(n) asm volatile("s_waitcnt vmcnt(" #n ")" ::: "memory")
; #define PG8_WAIT_L(n) asm volatile("s_waitcnt lgkmcnt(" #n ")" ::: "memory")
; #define PG8_BAR __builtin_amdgcn_s_barrier()
; #define PG8_SCHED __builtin_amdgcn_sched_barrier(0)
; template <class Epi, class Sched, bool ALIGN_EPI = false, bool SP2 = false, bool F16 = false>
; __device__ __forceinline__ void gemm_phase(PG8_LAS unsigned char* lds, const Gemm g, const Sched& S, const Epi& E) {
;     ...
;             PG8_WAIT_V(8); PG8_WAIT_L(0); PG8_BAR; PG8_MMA(1, 0, At, B0); PG8_MMA(1, 1, At, B1); PG8_BAR; PG8_SCHED;
;             PG8_LDB(B0, 1, 0); PG8_LDB(B1, 1, 1); PG8_SCHED; PG8_LDA(At, 1, 0); PG8_STAGE(PG8_SA(0, 1), a2 + hstep, voffA);
;             PG8_WAIT_V(8); PG8_WAIT_L(0); PG8_BAR; PG8_MMA(0, 0, At, B0); PG8_MMA(0, 1, At, B1); PG8_BAR; PG8_SCHED;
;             PG8_LDA(At, 1, 1); PG8_STAGE(PG8_SB(1, 0), b3, voffB); PG8_STAGE(PG8_SB(1, 1), b3 + hstep, voffB); PG8_STAGE(PG8_SA(1, 0), a3, voffA);
	s_setprio 1
	s_waitcnt lgkmcnt(0)
	v_mfma_f32_16x16x32_f16 v[76:79], v[32:35], v[194:197], 0
	v_mfma_f32_16x16x32_f16 v[72:75], v[40:43], v[194:197], 0
	v_mfma_f32_16x16x32_f16 v[60:63], v[32:35], v[202:205], 0
	v_mfma_f32_16x16x32_f16 v[56:59], v[40:43], v[202:205], 0
	v_mfma_f32_16x16x32_f16 v[28:31], v[32:35], v[210:213], 0
	v_mfma_f32_16x16x32_f16 v[24:27], v[40:43], v[210:213], 0
	v_mfma_f32_16x16x32_f16 v[12:15], v[32:35], v[218:221], 0
	v_mfma_f32_16x16x32_f16 v[8:11], v[40:43], v[218:221], 0
	v_mfma_f32_16x16x32_f16 v[76:79], v[36:39], v[198:201], v[76:79]
	v_mfma_f32_16x16x32_f16 v[72:75], v[44:47], v[198:201], v[72:75]
	v_mfma_f32_16x16x32_f16 v[60:63], v[36:39], v[206:209], v[60:63]
	v_mfma_f32_16x16x32_f16 v[56:59], v[44:47], v[206:209], v[56:59]
	v_mfma_f32_16x16x32_f16 v[28:31], v[36:39], v[214:217], v[28:31]
	v_mfma_f32_16x16x32_f16 v[24:27], v[44:47], v[214:217], v[24:27]
	v_mfma_f32_16x16x32_f16 v[12:15], v[36:39], v[222:225], v[12:15]
	v_mfma_f32_16x16x32_f16 v[8:11], v[44:47], v[222:225], v[8:11]
	v_mfma_f32_16x16x32_f16 v[20:23], v[156:159], v[210:213], 0
	v_mfma_f32_16x16x32_f16 v[16:19], v[186:189], v[210:213], 0
	v_mfma_f32_16x16x32_f16 v[4:7], v[156:159], v[218:221], 0
	v_mfma_f32_16x16x32_f16 v[0:3], v[186:189], v[218:221], 0
	v_mfma_f32_16x16x32_f16 v[32:35], v[156:159], v[194:197], 0
	v_mfma_f32_16x16x32_f16 v[36:39], v[186:189], v[194:197], 0
	v_mfma_f32_16x16x32_f16 v[40:43], v[156:159], v[202:205], 0
	v_mfma_f32_16x16x32_f16 v[44:47], v[186:189], v[202:205], 0
	v_mfma_f32_16x16x32_f16 v[20:23], v[168:171], v[214:217], v[20:23]
	v_mfma_f32_16x16x32_f16 v[16:19], v[190:193], v[214:217], v[16:19]
	v_mfma_f32_16x16x32_f16 v[4:7], v[168:171], v[222:225], v[4:7]
	v_mfma_f32_16x16x32_f16 v[0:3], v[190:193], v[222:225], v[0:3]
	v_mfma_f32_16x16x32_f16 v[32:35], v[168:171], v[198:201], v[32:35]
	v_mfma_f32_16x16x32_f16 v[36:39], v[190:193], v[198:201], v[36:39]
	v_mfma_f32_16x16x32_f16 v[40:43], v[168:171], v[206:209], v[40:43]
	v_mfma_f32_16x16x32_f16 v[44:47], v[190:193], v[206:209], v[44:47]
	s_setprio 0
	s_barrier
	s_add_i32 s62, 0, 0x18000
	s_add_i32 s63, 0, 0x1c000
	ds_read_b128 v[48:51], v172 offset:32768
	ds_read_b128 v[52:55], v172 offset:33792
	ds_read_b128 v[64:67], v172 offset:34816
	ds_read_b128 v[68:71], v172 offset:35840
	ds_read_b128 v[156:159], v172 offset:49152
	ds_read_b128 v[168:171], v172 offset:50176
	ds_read_b128 v[186:189], v172 offset:51200
	ds_read_b128 v[190:193], v172 offset:52224
	s_add_u32 s58, s58, 0x40000
	s_addc_u32 s59, s59, 0
	s_mov_b32 m0, s11
	ds_read_b128 v[194:197], v165 offset:32768
	ds_read_b128 v[198:201], v165 offset:33792
	ds_read_b128 v[202:205], v165 offset:34816
	ds_read_b128 v[206:209], v165 offset:35840
	ds_read_b128 v[210:213], v165 offset:36864
	ds_read_b128 v[214:217], v165 offset:37888
	ds_read_b128 v[218:221], v165 offset:38912
	ds_read_b128 v[222:225], v165 offset:39936
	global_load_lds_dwordx4 v150, s[58:59]
	s_mov_b32 m0, s13
	s_nop 0
	global_load_lds_dwordx4 v148, s[58:59]
	s_waitcnt vmcnt(8)
	s_waitcnt lgkmcnt(0)
	s_barrier
	s_setprio 1
	s_waitcnt lgkmcnt(0)
	v_mfma_f32_16x16x32_f16 v[142:145], v[48:51], v[194:197], v[142:145]
	v_mfma_f32_16x16x32_f16 v[138:141], v[64:67], v[194:197], v[138:141]
	v_mfma_f32_16x16x32_f16 v[124:127], v[48:51], v[202:205], v[124:127]
	v_mfma_f32_16x16x32_f16 v[120:123], v[64:67], v[202:205], v[120:123]
	v_mfma_f32_16x16x32_f16 v[108:111], v[48:51], v[210:213], v[108:111]
	v_mfma_f32_16x16x32_f16 v[104:107], v[64:67], v[210:213], v[104:107]
	v_mfma_f32_16x16x32_f16 v[92:95], v[48:51], v[218:221], v[92:95]
	v_mfma_f32_16x16x32_f16 v[88:91], v[64:67], v[218:221], v[88:91]
	v_mfma_f32_16x16x32_f16 v[142:145], v[52:55], v[198:201], v[142:145]
	v_mfma_f32_16x16x32_f16 v[138:141], v[68:71], v[198:201], v[138:141]
	v_mfma_f32_16x16x32_f16 v[124:127], v[52:55], v[206:209], v[124:127]
	v_mfma_f32_16x16x32_f16 v[120:123], v[68:71], v[206:209], v[120:123]
	v_mfma_f32_16x16x32_f16 v[108:111], v[52:55], v[214:217], v[108:111]
	v_mfma_f32_16x16x32_f16 v[104:107], v[68:71], v[214:217], v[104:107]
	v_mfma_f32_16x16x32_f16 v[92:95], v[52:55], v[222:225], v[92:95]
	v_mfma_f32_16x16x32_f16 v[88:91], v[68:71], v[222:225], v[88:91]
	v_mfma_f32_16x16x32_f16 v[134:137], v[156:159], v[194:197], v[134:137]
	v_mfma_f32_16x16x32_f16 v[130:133], v[186:189], v[194:197], v[130:133]
	v_mfma_f32_16x16x32_f16 v[116:119], v[156:159], v[202:205], v[116:119]
	v_mfma_f32_16x16x32_f16 v[112:115], v[186:189], v[202:205], v[112:115]
	v_mfma_f32_16x16x32_f16 v[100:103], v[156:159], v[210:213], v[100:103]
	v_mfma_f32_16x16x32_f16 v[96:99], v[186:189], v[210:213], v[96:99]
	v_mfma_f32_16x16x32_f16 v[84:87], v[156:159], v[218:221], v[84:87]
	v_mfma_f32_16x16x32_f16 v[80:83], v[186:189], v[218:221], v[80:83]
	v_mfma_f32_16x16x32_f16 v[134:137], v[168:171], v[198:201], v[134:137]
	v_mfma_f32_16x16x32_f16 v[130:133], v[190:193], v[198:201], v[130:133]
	v_mfma_f32_16x16x32_f16 v[116:119], v[168:171], v[206:209], v[116:119]
	v_mfma_f32_16x16x32_f16 v[112:115], v[190:193], v[206:209], v[112:115]
	v_mfma_f32_16x16x32_f16 v[100:103], v[168:171], v[214:217], v[100:103]
	v_mfma_f32_16x16x32_f16 v[96:99], v[190:193], v[214:217], v[96:99]
	v_mfma_f32_16x16x32_f16 v[84:87], v[168:171], v[222:225], v[84:87]
	v_mfma_f32_16x16x32_f16 v[80:83], v[190:193], v[222:225], v[80:83]
	s_setprio 0
	s_barrier
; #define PG8_STAGE(bufoff, gbase, voff) do { _Pragma("unroll") for (int _i = 0; _i < 2; ++_i) \
;         __builtin_amdgcn_global_load_lds((const unsigned*)((const char*)(gbase) + (voff)[_i]), (PG8_LAS unsigned*)(lds + (bufoff) + ldsw + _i * 8192), 16, 0, 0); } while (0)
; #define PG8_LDA(dst, b, h) do { _Pragma("unroll") for (int m = 0; m < 4; ++m) _Pragma("unroll") for (int k = 0; k < 2; ++k) dst[m][k] = *(const PG8_LAS bf16x8*)(lds + PG8_SA(b, h) + aoff + m * 2048 + k * 1024); } while (0)
; #define PG8_MMA(ai, bj, At, Bt) do { __builtin_amdgcn_s_setprio(1); _Pragma("unroll") for (int m = 0; m < 4; ++m) _Pragma("unroll") for (int n = 0; n < 2; ++n) _Pragma("unroll") for (int k = 0; k < 2; ++k) \
;         acc[ai][bj][m][n] = mma16<F16>(Bt[n][k], At[m][k], acc[ai][bj][m][n]); __builtin_amdgcn_s_setprio(0); } while (0)
; #define PG8_WAIT_V(n) asm volatile("s_waitcnt vmcnt(" #n ")" ::: "memory")
; #define PG8_WAIT_L(n) asm volatile("s_waitcnt lgkmcnt(" #n ")" ::: "memory")
; #define PG8_BAR __builtin_amdgcn_s_barrier()
; #define PG8_SCHED __builtin_amdgcn_sched_barrier(0)
; template <class Epi, class Sched, bool ALIGN_EPI = false, bool SP2 = false, bool F16 = false>
; __device__ __forceinline__ void gemm_phase(PG8_LAS unsigned char* lds, const Gemm g, const Sched& S, const Epi& E) {
;     ...
;             PG8_LDA(At, 1, 1); PG8_STAGE(PG8_SB(1, 0), b3, voffB); PG8_STAGE(PG8_SB(1, 1), b3 + hstep, voffB); PG8_STAGE(PG8_SA(1, 0), a3, voffA);
;             PG8_WAIT_V(8); PG8_WAIT_L(0); PG8_BAR; PG8_MMA(1, 0, At, B0); PG8_MMA(1, 1, At, B1); PG8_BAR; PG8_SCHED;
	s_add_i32 s58, s62, s8
	s_mov_b32 m0, s58
	ds_read_b128 v[194:197], v165 offset:49152
	ds_read_b128 v[198:201], v165 offset:50176
	ds_read_b128 v[202:205], v165 offset:51200
	ds_read_b128 v[206:209], v165 offset:52224
	ds_read_b128 v[210:213], v165 offset:53248
	ds_read_b128 v[214:217], v165 offset:54272
	ds_read_b128 v[218:221], v165 offset:55296
	ds_read_b128 v[222:225], v165 offset:56320
	global_load_lds_dwordx4 v128, s[98:99]
	s_add_i32 m0, s58, 0x2000
	s_add_u32 s56, s56, 0x40080
	s_addc_u32 s57, s57, 0
	s_add_i32 s58, s63, s8
	global_load_lds_dwordx4 v146, s[98:99]
	s_mov_b32 m0, s58
	s_nop 0
	global_load_lds_dwordx4 v128, s[56:57]
	s_add_i32 m0, s58, 0x2000
	s_nop 0
	global_load_lds_dwordx4 v146, s[56:57]
	s_mov_b32 m0, s20
	s_nop 0
	global_load_lds_dwordx4 v150, s[100:101]
	s_mov_b32 m0, s21
	s_nop 0
	global_load_lds_dwordx4 v148, s[100:101]
	s_waitcnt vmcnt(8)
	s_waitcnt lgkmcnt(0)
	s_barrier
	s_setprio 1
	s_waitcnt lgkmcnt(0)
	v_mfma_f32_16x16x32_f16 v[76:79], v[48:51], v[194:197], v[76:79]
	v_mfma_f32_16x16x32_f16 v[72:75], v[64:67], v[194:197], v[72:75]
	v_mfma_f32_16x16x32_f16 v[60:63], v[48:51], v[202:205], v[60:63]
	v_mfma_f32_16x16x32_f16 v[56:59], v[64:67], v[202:205], v[56:59]
	v_mfma_f32_16x16x32_f16 v[28:31], v[48:51], v[210:213], v[28:31]
	v_mfma_f32_16x16x32_f16 v[24:27], v[64:67], v[210:213], v[24:27]
	v_mfma_f32_16x16x32_f16 v[12:15], v[48:51], v[218:221], v[12:15]
	v_mfma_f32_16x16x32_f16 v[8:11], v[64:67], v[218:221], v[8:11]
	v_mfma_f32_16x16x32_f16 v[76:79], v[52:55], v[198:201], v[76:79]
	v_mfma_f32_16x16x32_f16 v[72:75], v[68:71], v[198:201], v[72:75]
	v_mfma_f32_16x16x32_f16 v[60:63], v[52:55], v[206:209], v[60:63]
	v_mfma_f32_16x16x32_f16 v[56:59], v[68:71], v[206:209], v[56:59]
	v_mfma_f32_16x16x32_f16 v[28:31], v[52:55], v[214:217], v[28:31]
	v_mfma_f32_16x16x32_f16 v[24:27], v[68:71], v[214:217], v[24:27]
	v_mfma_f32_16x16x32_f16 v[12:15], v[52:55], v[222:225], v[12:15]
	v_mfma_f32_16x16x32_f16 v[8:11], v[68:71], v[222:225], v[8:11]
	v_mfma_f32_16x16x32_f16 v[32:35], v[156:159], v[194:197], v[32:35]
	v_mfma_f32_16x16x32_f16 v[68:71], v[168:171], v[198:201], v[32:35]
	v_mfma_f32_16x16x32_f16 v[32:35], v[186:189], v[194:197], v[36:39]
	v_mfma_f32_16x16x32_f16 v[64:67], v[190:193], v[198:201], v[32:35]
	v_mfma_f32_16x16x32_f16 v[32:35], v[156:159], v[202:205], v[40:43]
	v_mfma_f32_16x16x32_f16 v[52:55], v[168:171], v[206:209], v[32:35]
	v_mfma_f32_16x16x32_f16 v[32:35], v[186:189], v[202:205], v[44:47]
	v_mfma_f32_16x16x32_f16 v[20:23], v[156:159], v[210:213], v[20:23]
	v_mfma_f32_16x16x32_f16 v[16:19], v[186:189], v[210:213], v[16:19]
	v_mfma_f32_16x16x32_f16 v[4:7], v[156:159], v[218:221], v[4:7]
	v_mfma_f32_16x16x32_f16 v[0:3], v[186:189], v[218:221], v[0:3]
	v_mfma_f32_16x16x32_f16 v[48:51], v[190:193], v[206:209], v[32:35]
	v_mfma_f32_16x16x32_f16 v[20:23], v[168:171], v[214:217], v[20:23]
	v_mfma_f32_16x16x32_f16 v[16:19], v[190:193], v[214:217], v[16:19]
	v_mfma_f32_16x16x32_f16 v[4:7], v[168:171], v[222:225], v[4:7]
	v_mfma_f32_16x16x32_f16 v[0:3], v[190:193], v[222:225], v[0:3]
	s_setprio 0
	s_barrier
	s_add_i32 s61, s61, 2
	s_add_u32 s54, s54, 0x100
	s_addc_u32 s55, s55, 0
	s_add_u32 s49, s49, 0x100
	s_addc_u32 s60, s60, 0
	s_cmp_gt_u32 s61, 13
